# P3 cmp pacing stride 4 on the LDS-staged cmp task version (all other changes kept)
# speedup vs baseline: 1.0032x; 1.0030x over previous
; DI void cmp_task(const bf16_t* Z, const bf16_t* KCC, const bf16_t* VCT, bf16_t* OCMP, unsigned* selm, int b, int hk, int tg, int lane) {
;     ...
; #pragma unroll
;         for (int mm = 0; mm < 4; ++mm) {
;             const int jm = 8 * g + 2 * mm + h; const float v = mine[mm]; int rank = 0;
; #pragma unroll
;             for (int T = 0; T < 4; ++T)
; #pragma unroll
;                 for (int m2 = 0; m2 < 4; ++m2) { const int je = 8 * T + 2 * m2;
;                     rank += (ev[T][m2] > v || (ev[T][m2] == v && je < jm)) ? 1 : 0; rank += (od[T][m2] > v || (od[T][m2] == v && je + 1 < jm)) ? 1 : 0; }
;             if (v >= 0.f && rank < 5) word |= 1u << jm;
; __global__ void __launch_bounds__(NTHR, 2) fwd_kernel(Args a) {
;     ...
;     {
;         const int nrow = (MTOK - gw + NGW - 1) / NGW, ncmp = (8192 - gw + NGW - 1) / NGW;
;         const int stride = nrow > 0 && ncmp > 0 ? (nrow / ncmp > 0 ? nrow / ncmp : 1) : 1, phase = ((wave >> 2) * (stride >> 1) + (wave & 1)) % stride;
;         int ci = 0;
;         for (int i = 0; i < nrow || ci < ncmp; ++i) {
;             if (ci < ncmp && (i >= nrow || (i % stride) == phase)) { const int task = gw + ci * NGW; ++ci;
.LBB0_474:
	v_cvt_f32_u32_e32 v1, s69
	s_add_u32 s21, s18, 0x6000000
	s_addc_u32 s68, s19, 0
	s_add_u32 s12, s18, 0x6800000
	v_rcp_iflag_f32_e32 v1, v1
	s_addc_u32 s13, s19, 0
	s_or_b64 s[4:5], s[8:9], s[10:11]
	s_andn2_b64 vcc, exec, s[4:5]
	v_mul_f32_e32 v1, 0x4f7ffffe, v1
	v_cvt_u32_f32_e32 v1, v1
	s_nop 0
	v_readfirstlane_b32 s59, v1
	s_cbranch_vccnz .LBB0_659
	v_lshlrev_b32_e32 v1, 6, v133
	v_or_b32_e32 v37, 47, v1
	v_or_b32_e32 v46, 31, v1
	v_or_b32_e32 v117, 63, v1
	v_add_u32_e32 v119, 0x4f, v1
	v_or_b32_e32 v39, 0xaf, v1
	v_or_b32_e32 v48, 0x9f, v1
	v_or_b32_e32 v202, 0xbf, v1
	v_add_u32_e32 v203, 0xcf, v1
	v_or_b32_e32 v47, 0x12f, v1
	v_or_b32_e32 v50, 0x11f, v1
	v_or_b32_e32 v204, 0x13f, v1
	v_add_u32_e32 v205, 0x14f, v1
	v_or_b32_e32 v49, 0x1af, v1
	v_or_b32_e32 v52, 0x19f, v1
	v_or_b32_e32 v206, 0x1bf, v1
	v_add_u32_e32 v207, 0x1cf, v1
	v_or_b32_e32 v51, 0x22f, v1
	v_or_b32_e32 v54, 0x21f, v1
	v_or_b32_e32 v208, 0x23f, v1
	v_add_u32_e32 v209, 0x24f, v1
	v_or_b32_e32 v53, 0x2af, v1
	v_or_b32_e32 v56, 0x29f, v1
	v_or_b32_e32 v210, 0x2bf, v1
	v_add_u32_e32 v211, 0x2cf, v1
	v_or_b32_e32 v55, 0x32f, v1
	v_or_b32_e32 v58, 0x31f, v1
	v_or_b32_e32 v212, 0x33f, v1
	v_add_u32_e32 v213, 0x34f, v1
	v_or_b32_e32 v57, 0x3af, v1
	v_or_b32_e32 v60, 0x39f, v1
	v_or_b32_e32 v216, 0x3bf, v1
	v_add_u32_e32 v217, 0x3cf, v1
	v_or_b32_e32 v59, 0x42f, v1
	v_or_b32_e32 v62, 0x41f, v1
	v_or_b32_e32 v218, 0x43f, v1
	v_add_u32_e32 v219, 0x44f, v1
	v_or_b32_e32 v61, 0x4af, v1
	v_or_b32_e32 v64, 0x49f, v1
	v_or_b32_e32 v220, 0x4bf, v1
	v_add_u32_e32 v221, 0x4cf, v1
	v_or_b32_e32 v63, 0x52f, v1
	v_or_b32_e32 v66, 0x51f, v1
	v_or_b32_e32 v222, 0x53f, v1
	v_add_u32_e32 v223, 0x54f, v1
	v_or_b32_e32 v65, 0x5af, v1
	v_or_b32_e32 v68, 0x59f, v1
	v_or_b32_e32 v224, 0x5bf, v1
	v_add_u32_e32 v225, 0x5cf, v1
	v_or_b32_e32 v67, 0x62f, v1
	v_or_b32_e32 v70, 0x61f, v1
	v_or_b32_e32 v226, 0x63f, v1
	v_add_u32_e32 v227, 0x64f, v1
	v_or_b32_e32 v69, 0x6af, v1
	v_or_b32_e32 v72, 0x69f, v1
	v_or_b32_e32 v228, 0x6bf, v1
	v_add_u32_e32 v229, 0x6cf, v1
	v_or_b32_e32 v71, 0x72f, v1
	v_or_b32_e32 v74, 0x71f, v1
	v_or_b32_e32 v230, 0x73f, v1
	v_add_u32_e32 v231, 0x74f, v1
	v_or_b32_e32 v73, 0x7af, v1
	v_or_b32_e32 v76, 0x79f, v1
	v_or_b32_e32 v232, 0x7bf, v1
	v_add_u32_e32 v233, 0x7cf, v1
	v_lshl_or_b32 v1, v214, 3, v133
	v_cmp_lt_u32_e64 s[16:17], 2, v1
	v_cmp_lt_u32_e64 s[26:27], 10, v1
	v_cmp_lt_u32_e64 s[38:39], 18, v1
	v_writelane_b32 v253, s16, 6
	v_mov_b32_e32 v43, 0
	v_lshlrev_b32_e32 v40, 1, v139
	v_writelane_b32 v253, s17, 7
	v_cmp_lt_u32_e64 s[16:17], 4, v1
	v_mov_b32_e32 v41, v43
	v_or_b32_e32 v2, 2, v1
	v_writelane_b32 v253, s16, 8
	v_lshl_add_u64 v[44:45], s[48:49], 0, v[40:41]
	v_cmp_lt_u32_e64 s[48:49], 4, v2
	v_writelane_b32 v253, s17, 9
	v_cmp_lt_u32_e64 s[16:17], 6, v1
	s_lshr_b32 s4, s78, 8
	s_lshr_b32 s5, s69, 1
	v_writelane_b32 v253, s16, 10
	s_mul_i32 s4, s5, s4
	s_bfe_u32 s5, s78, 0x10006
	v_writelane_b32 v253, s17, 11
	v_cmp_lt_u32_e64 s[16:17], 8, v1
	s_add_i32 s4, s4, s5
	s_sub_i32 s5, 0, s69
	v_writelane_b32 v253, s16, 12
	s_mul_i32 s5, s5, s59
	s_mul_hi_u32 s5, s59, s5
	v_writelane_b32 v253, s17, 13
	v_writelane_b32 v253, s26, 14
	s_add_i32 s59, s59, s5
	s_mul_hi_u32 s5, s4, s59
	v_writelane_b32 v253, s27, 15
	v_cmp_lt_u32_e64 s[26:27], 12, v1
	s_mul_i32 s5, s5, s69
	s_sub_i32 s4, s4, s5
	v_writelane_b32 v253, s26, 16
	s_sub_i32 s5, s4, s69
	s_cmp_ge_u32 s4, s69
	v_writelane_b32 v253, s27, 17
	v_cmp_lt_u32_e64 s[26:27], 14, v1
	s_cselect_b32 s4, s5, s4
	s_sub_i32 s5, s4, s69
	v_writelane_b32 v253, s26, 18
	v_cmp_ne_u32_e64 s[6:7], 0, v1
	v_lshlrev_b32_e64 v237, v1, 1
	v_writelane_b32 v253, s27, 19
	v_cmp_lt_u32_e64 s[26:27], 16, v1
	v_lshlrev_b32_e64 v238, v1, 4
	v_lshlrev_b32_e64 v239, v1, 16
	v_writelane_b32 v253, s26, 20
	v_lshlrev_b32_e64 v240, v1, 64
	s_cmp_ge_u32 s4, s69
	v_writelane_b32 v253, s27, 21
	v_writelane_b32 v253, s38, 22
	v_mov_b32_e32 v139, v43
	v_lshlrev_b32_e32 v88, 2, v135
	v_writelane_b32 v253, s39, 23
	v_cmp_lt_u32_e64 s[38:39], 20, v1
	v_lshlrev_b32_e32 v241, 2, v242
	v_cmp_eq_u32_e64 s[74:75], 0, v242
	v_writelane_b32 v253, s38, 24
	v_lshlrev_b32_e32 v242, 5, v135
	s_cselect_b32 s60, s5, s4
	v_writelane_b32 v253, s39, 25
	v_cmp_lt_u32_e64 s[38:39], 22, v1
	v_lshrrev_b32_e32 v113, 2, v134
	v_lshlrev_b32_e32 v115, 6, v214
	v_writelane_b32 v253, s38, 26
	v_lshlrev_b32_e32 v38, 6, v134
	v_lshl_add_u64 v[78:79], s[14:15], 0, v[138:139]
	v_writelane_b32 v253, s39, 27
	v_writelane_b32 v253, s48, 28
	v_cmp_eq_u32_e64 s[38:39], 25, v1
	v_or_b32_e32 v80, 0x1000, v136
	v_writelane_b32 v253, s49, 29
	v_cmp_lt_u32_e64 s[48:49], 5, v2
	v_cmp_gt_u32_e64 s[4:5], 32, v135
	v_or_b32_e32 v84, 20, v133
	v_writelane_b32 v253, s48, 30
	v_or_b32_e32 v36, 18, v133
	v_or_b32_e32 v236, 24, v133
	v_writelane_b32 v253, s49, 31
	v_cmp_lt_u32_e64 s[48:49], 6, v2
	v_or_b32_e32 v81, 28, v133
	s_mov_b32 s15, 0
	v_writelane_b32 v253, s48, 32
	v_cmp_lt_u32_e64 s[16:17], 1, v214
	v_cmp_ne_u32_e64 s[26:27], 0, v214
	v_writelane_b32 v253, s49, 33
	v_cmp_lt_u32_e64 s[48:49], 8, v2
	v_cmp_eq_u32_e64 s[28:29], 3, v214
	v_or_b32_e32 v83, 0x101, v88
	v_writelane_b32 v253, s48, 34
	v_or_b32_e32 v90, 0x100, v88
	v_or_b32_e32 v85, 0x103, v88
	v_writelane_b32 v253, s49, 35
	v_cmp_lt_u32_e64 s[48:49], 9, v2
	v_or_b32_e32 v92, 0x102, v88
	v_or_b32_e32 v87, 0x201, v88
	v_writelane_b32 v253, s48, 36
	v_or_b32_e32 v86, 0x200, v88
	v_or_b32_e32 v89, 0x203, v88
	v_writelane_b32 v253, s49, 37
	v_cmp_lt_u32_e64 s[48:49], 10, v2
	v_or_b32_e32 v91, 0x301, v88
	v_or_b32_e32 v98, 0x300, v88
	v_writelane_b32 v253, s48, 38
	v_or_b32_e32 v93, 0x303, v88
	v_or_b32_e32 v100, 0x302, v88
; DI void cmp_task(const bf16_t* Z, const bf16_t* KCC, const bf16_t* VCT, bf16_t* OCMP, unsigned* selm, int b, int hk, int tg, int lane) {
;     ...
; #pragma unroll
;         for (int mm = 0; mm < 4; ++mm) {
;             const int jm = 8 * g + 2 * mm + h; const float v = mine[mm]; int rank = 0;
; #pragma unroll
;             for (int T = 0; T < 4; ++T)
; #pragma unroll
;                 for (int m2 = 0; m2 < 4; ++m2) { const int je = 8 * T + 2 * m2;
;                     rank += (ev[T][m2] > v || (ev[T][m2] == v && je < jm)) ? 1 : 0; rank += (od[T][m2] > v || (od[T][m2] == v && je + 1 < jm)) ? 1 : 0; }
;             if (v >= 0.f && rank < 5) word |= 1u << jm;
; __global__ void __launch_bounds__(NTHR, 2) fwd_kernel(Args a) {
;     ...
;         for (int i = 0; i < nrow || ci < ncmp; ++i) {
;             if (ci < ncmp && (i >= nrow || (i % stride) == phase)) { const int task = gw + ci * NGW; ++ci;
;                 cmp_task(Z, KCC, VCT, OCMP, SELM, task >> 9, (task >> 8) & 1, (task + 64 * (task >> 11)) & 255, lane); }
	v_writelane_b32 v253, s49, 39
	v_cmp_lt_u32_e64 s[48:49], 16, v2
	v_or_b32_e32 v102, 0x400, v88
	v_or_b32_e32 v104, 0x402, v88
	v_writelane_b32 v253, s48, 40
	v_or_b32_e32 v99, 0x501, v88
	v_or_b32_e32 v106, 0x500, v88
	v_writelane_b32 v253, s49, 41
	v_cmp_lt_u32_e64 s[48:49], 12, v2
	v_or_b32_e32 v101, 0x503, v88
	v_or_b32_e32 v108, 0x502, v88
	v_writelane_b32 v253, s48, 42
	v_or_b32_e32 v103, 0x601, v88
	v_or_b32_e32 v110, 0x600, v88
	v_writelane_b32 v253, s49, 43
	v_cmp_lt_u32_e64 s[48:49], 17, v2
	v_or_b32_e32 v105, 0x603, v88
	v_or_b32_e32 v112, 0x602, v88
	v_writelane_b32 v253, s48, 44
	v_or_b32_e32 v107, 0x701, v88
	v_or_b32_e32 v114, 0x700, v88
	v_writelane_b32 v253, s49, 45
	v_cmp_lt_u32_e64 s[48:49], 13, v2
	v_or_b32_e32 v109, 0x703, v88
	v_or_b32_e32 v116, 0x702, v88
	v_writelane_b32 v253, s48, 46
	v_or_b32_e32 v243, 31, v242
	s_mov_b32 s46, 0x3e38aa3b
	v_writelane_b32 v253, s49, 47
	v_cmp_lt_u32_e64 s[48:49], 18, v2
	s_mov_b32 s61, 0xff800000
	s_mov_b32 s62, -1.0
	v_writelane_b32 v253, s48, 48
	v_lshlrev_b32_e32 v120, 2, v88
	v_mov_b32_e32 v244, 0x2200
	v_writelane_b32 v253, s49, 49
	v_cmp_lt_u32_e64 s[48:49], 14, v2
	v_mov_b32_e32 v245, 0xff800000
	s_mov_b32 s63, 0
	v_writelane_b32 v253, s48, 50
	s_mov_b32 s64, 0
	s_nop 0
	v_writelane_b32 v253, s49, 51
	v_cmp_lt_u32_e64 s[48:49], 20, v2
	s_nop 1
	v_writelane_b32 v253, s48, 52
	s_nop 1
	v_writelane_b32 v253, s49, 53
	v_cmp_lt_u32_e64 s[48:49], 21, v2
	s_nop 1
	v_writelane_b32 v253, s48, 54
	s_nop 1
	v_writelane_b32 v253, s49, 55
	v_cmp_lt_u32_e64 s[48:49], 22, v2
	s_nop 1
	v_writelane_b32 v253, s48, 56
	s_nop 1
	v_writelane_b32 v253, s49, 57
	v_cmp_lt_u32_e64 s[48:49], 24, v2
	s_nop 1
	v_writelane_b32 v253, s48, 58
	s_nop 1
	v_writelane_b32 v253, s49, 59
	v_cmp_lt_u32_e64 s[48:49], 25, v2
	v_or_b32_e32 v2, 4, v1
	s_nop 0
	v_writelane_b32 v253, s48, 60
	s_nop 1
	v_writelane_b32 v253, s49, 61
	v_cmp_lt_u32_e64 s[48:49], 5, v2
	s_nop 1
	v_writelane_b32 v253, s48, 62
	s_nop 1
	v_writelane_b32 v253, s49, 63
	v_cmp_lt_u32_e64 s[48:49], 6, v2
	s_nop 1
	v_writelane_b32 v254, s48, 0
	s_nop 1
	v_writelane_b32 v254, s49, 1
	v_cmp_lt_u32_e64 s[48:49], 8, v2
	s_nop 1
	v_writelane_b32 v254, s48, 2
	s_nop 1
	v_writelane_b32 v254, s49, 3
	v_cmp_lt_u32_e64 s[48:49], 9, v2
	s_nop 1
	v_writelane_b32 v254, s48, 4
	s_nop 1
	v_writelane_b32 v254, s49, 5
	v_cmp_lt_u32_e64 s[48:49], 10, v2
	s_nop 1
	v_writelane_b32 v254, s48, 6
	s_nop 1
	v_writelane_b32 v254, s49, 7
	v_cmp_lt_u32_e64 s[48:49], 11, v2
	s_nop 1
	v_writelane_b32 v254, s48, 8
	s_nop 1
	v_writelane_b32 v254, s49, 9
	v_cmp_lt_u32_e64 s[48:49], 12, v2
	s_nop 1
	v_writelane_b32 v254, s48, 10
	s_nop 1
	v_writelane_b32 v254, s49, 11
	v_cmp_lt_u32_e64 s[48:49], 13, v2
	s_nop 1
	v_writelane_b32 v254, s48, 12
	s_nop 1
	v_writelane_b32 v254, s49, 13
	v_cmp_lt_u32_e64 s[48:49], 14, v2
	s_nop 1
	v_writelane_b32 v254, s48, 14
	s_nop 1
	v_writelane_b32 v254, s49, 15
	v_cmp_lt_u32_e64 s[48:49], 16, v2
	s_nop 1
	v_writelane_b32 v254, s48, 16
	s_nop 1
	v_writelane_b32 v254, s49, 17
	v_cmp_lt_u32_e64 s[48:49], 17, v2
	s_nop 1
	v_writelane_b32 v254, s48, 18
	s_nop 1
	v_writelane_b32 v254, s49, 19
	v_cmp_lt_u32_e64 s[48:49], 18, v2
	s_nop 1
	v_writelane_b32 v254, s48, 20
	s_nop 1
	v_writelane_b32 v254, s49, 21
	v_cmp_lt_u32_e64 s[48:49], 19, v2
	s_nop 1
	v_writelane_b32 v254, s48, 22
	s_nop 1
	v_writelane_b32 v254, s49, 23
	v_cmp_lt_u32_e64 s[48:49], 20, v2
	s_nop 1
	v_writelane_b32 v254, s48, 24
	s_nop 1
	v_writelane_b32 v254, s49, 25
	v_cmp_lt_u32_e64 s[48:49], 21, v2
	s_nop 1
	v_writelane_b32 v254, s48, 26
	s_nop 1
	v_writelane_b32 v254, s49, 27
	v_cmp_lt_u32_e64 s[48:49], 22, v2
	s_nop 1
	v_writelane_b32 v254, s48, 28
	s_nop 1
	v_writelane_b32 v254, s49, 29
	v_cmp_lt_u32_e64 s[48:49], 24, v2
	s_nop 1
	v_writelane_b32 v254, s48, 30
	s_nop 1
	v_writelane_b32 v254, s49, 31
	v_cmp_lt_u32_e64 s[48:49], 25, v2
	s_nop 1
	v_writelane_b32 v254, s48, 32
	s_nop 1
	v_writelane_b32 v254, s49, 33
	v_cmp_lt_u32_e64 s[48:49], 26, v2
	s_nop 1
	v_writelane_b32 v254, s48, 34
	s_nop 1
	v_writelane_b32 v254, s49, 35
	v_cmp_lt_u32_e64 s[48:49], 27, v2
	v_or_b32_e32 v2, 6, v1
	v_and_b32_e32 v1, 35, v0
	v_writelane_b32 v254, s48, 36
	v_cmp_lt_u32_e64 s[70:71], 29, v2
	v_cmp_eq_u32_e64 s[72:73], 0, v1
	v_writelane_b32 v254, s49, 37
	v_cmp_lt_u32_e64 s[48:49], 8, v2
	v_mbcnt_lo_u32_b32 v1, -1, 0
	v_mbcnt_hi_u32_b32 v246, -1, v1
	v_writelane_b32 v254, s48, 38
	s_nop 1
	v_writelane_b32 v254, s49, 39
	v_cmp_lt_u32_e64 s[48:49], 9, v2
	s_nop 1
	v_writelane_b32 v254, s48, 40
	s_nop 1
	v_writelane_b32 v254, s49, 41
	v_cmp_lt_u32_e64 s[48:49], 10, v2
	s_nop 1
	v_writelane_b32 v254, s48, 42
	s_nop 1
	v_writelane_b32 v254, s49, 43
	v_cmp_lt_u32_e64 s[48:49], 11, v2
	s_nop 1
	v_writelane_b32 v254, s48, 44
	s_nop 1
	v_writelane_b32 v254, s49, 45
	v_cmp_lt_u32_e64 s[48:49], 12, v2
	s_nop 1
	v_writelane_b32 v254, s48, 46
	s_nop 1
	v_writelane_b32 v254, s49, 47
	v_cmp_lt_u32_e64 s[48:49], 13, v2
	s_nop 1
	v_writelane_b32 v254, s48, 48
	s_nop 1
	v_writelane_b32 v254, s49, 49
	v_cmp_lt_u32_e64 s[48:49], 14, v2
	s_nop 1
	v_writelane_b32 v254, s48, 50
	s_nop 1
	v_writelane_b32 v254, s49, 51
	v_cmp_lt_u32_e64 s[48:49], 16, v2
	s_nop 1
	v_writelane_b32 v254, s48, 52
	s_nop 1
	v_writelane_b32 v254, s49, 53
	v_cmp_lt_u32_e64 s[48:49], 17, v2
	s_nop 1
	v_writelane_b32 v254, s48, 54
	s_nop 1
	v_writelane_b32 v254, s49, 55
	v_cmp_lt_u32_e64 s[48:49], 18, v2
	s_nop 1
	v_writelane_b32 v254, s48, 56
	s_nop 1
	v_writelane_b32 v254, s49, 57
	v_cmp_lt_u32_e64 s[48:49], 19, v2
	s_nop 1
	v_writelane_b32 v254, s48, 58
	s_nop 1
	v_writelane_b32 v254, s49, 59
	v_cmp_lt_u32_e64 s[48:49], 20, v2
	s_nop 1
	v_writelane_b32 v254, s48, 60
	s_nop 1
	v_writelane_b32 v254, s49, 61
	v_cmp_lt_u32_e64 s[48:49], 21, v2
	s_nop 1
	v_writelane_b32 v254, s48, 62
	s_nop 1
	v_writelane_b32 v254, s49, 63
	v_cmp_lt_u32_e64 s[48:49], 22, v2
	s_nop 1
	v_writelane_b32 v255, s48, 0
	s_nop 1
	v_writelane_b32 v255, s49, 1
	v_cmp_lt_u32_e64 s[48:49], 24, v2
	s_nop 1
	v_writelane_b32 v255, s48, 2
	s_nop 1
	v_writelane_b32 v255, s49, 3
	v_cmp_lt_u32_e64 s[48:49], 25, v2
	s_nop 1
	v_writelane_b32 v255, s48, 4
	s_nop 1
	v_writelane_b32 v255, s49, 5
	v_cmp_lt_u32_e64 s[48:49], 26, v2
	s_nop 1
	v_writelane_b32 v255, s48, 6
	s_nop 1
	v_writelane_b32 v255, s49, 7
	v_cmp_lt_u32_e64 s[48:49], 27, v2
	s_nop 1
	v_writelane_b32 v255, s48, 8
	s_nop 1
	v_writelane_b32 v255, s49, 9
	v_cmp_lt_u32_e64 s[48:49], 28, v2
	v_lshlrev_b64 v[2:3], v135, -1
	v_not_b32_e32 v111, v3
	v_writelane_b32 v255, s48, 10
	v_not_b32_e32 v118, v2
	s_nop 0
	v_writelane_b32 v255, s49, 11
	s_mov_b64 s[48:49], exec
	s_mov_b64 exec, 1
	v_mov_b32_e32 v1, 0x20100
	v_mov_b32_e32 v2, 1
	ds_add_rtn_u32 v2, v1, v2
	s_waitcnt lgkmcnt(0)
	v_readfirstlane_b32 s47, v2
	s_mov_b64 exec, s[48:49]
	s_cmpk_lt_u32 s47, 0x80
	s_cselect_b64 s[8:9], -1, 0
	s_branch .LBB0_477
